# PN modulation-vector LDS reads issued at the top of the row; P0 transpose items handed out from the far end of the grid
# baseline (speedup 1.0000x reference)
; #define LAS __attribute__((address_space(3)))
; DI void phase0(const Params& p, LAS unsigned char* lds, int G, int bid) {
;     ...
;     LAS float* scr = (LAS float*)(lds + wave * 8704);
;     const int gw = bid * 8 + wave, NGW = G * 8;
;     constexpr int I_IN = 16 * 288, I_OUT = 32 * 32, I_L = I_IN + I_OUT;
;     for (int it = gw; it < 2 * I_L; it += NGW) {
;         const int l = it / I_L; int r = it % I_L;
;         if (r < I_IN) { const int kb = r / 288, nb = r % 288; const int n0 = nb * 32, tl_ = n0 >> 8, cl_ = n0 & 255;
;             const int cs = (tl_ >= 12 && tl_ < 20) ? ((cl_ < 128) ? 3072 + 128 * (tl_ - 12) + cl_ : 4096 + 128 * (tl_ - 12) + cl_ - 128) : (n0 < 5120 ? n0 : n0 + 8);
;             p0_transpose_item(p.w_in + (size_t)l * D * NSRC, NSRC, cs, D, (bf16_t*)(p.ws + WS_WIN) + (size_t)l * NPC * D, n0, kb * 64, scr, lane); }
;         else { r -= I_IN; const int kb = r / 32, nb = r % 32;
;             p0_transpose_item(p.w_out + (size_t)l * 2048 * D, D, nb * 32, 2048, (bf16_t*)(p.ws + WS_WOUT) + (size_t)l * D * 2048, nb * 32, kb * 64, scr, lane); }
;     }
.LBB0_25:
	s_sub_i32 s0, s94, s53
	s_add_i32 s0, s0, -1
	v_lshl_add_u32 v10, s0, 3, v1
	s_movk_i32 s0, 0x2c00
	v_cmp_gt_i32_e32 vcc, s0, v10
	s_waitcnt lgkmcnt(0)
	s_barrier
	s_and_saveexec_b64 s[0:1], vcc
	s_cbranch_execz .LBB0_40
	s_movk_i32 s10, 0x2200
	s_lshl_b32 s18, s94, 3
	v_mul_lo_u32 v1, v1, s10
	s_add_u32 s4, s92, 0x3400000
	v_add_u32_e32 v5, 0, v1
	v_lshrrev_b32_e32 v1, 5, v116
	v_and_b32_e32 v2, 31, v114
	v_lshlrev_b32_e32 v4, 3, v116
	s_addc_u32 s5, s93, 0
	v_lshl_add_u32 v6, v2, 2, v5
	v_mul_u32_u24_e32 v7, 0x84, v1
	v_lshrrev_b32_e32 v11, 3, v116
	v_and_b32_e32 v4, 56, v4
	s_add_u32 s8, s92, 0x1000000
	v_mul_u32_u24_e32 v8, 0x84, v4
	v_lshlrev_b32_e32 v9, 2, v11
	v_add_u32_e32 v18, v6, v7
	s_addc_u32 s9, s93, 0
	v_mov_b32_e32 v3, 0
	v_add3_u32 v12, v5, v8, v9
	v_or_b32_e32 v13, 8, v11
	v_or_b32_e32 v14, 16, v11
	v_or_b32_e32 v15, 24, v11
	v_lshlrev_b32_e32 v16, 1, v10
	s_lshl_b32 s19, s94, 4
	v_lshlrev_b32_e32 v17, 5, v10
	s_lshl_b32 s20, s94, 8
	s_mov_b64 s[10:11], 0
	s_movk_i32 s21, 0x600
	s_mov_b32 s22, 0x2408000
	s_mov_b32 s23, 0x1200000
	s_mov_b32 s24, 0x12000
	s_mov_b32 s25, 0x24000
	s_mov_b32 s27, 0x36000
	s_mov_b32 s28, 0x48000
	s_mov_b32 s29, 0x5a000
	s_mov_b32 s30, 0x6c000
	s_mov_b32 s31, 0x7e000
	s_mov_b32 s33, 0x90000
	s_mov_b32 s34, 0xa2000
	s_mov_b32 s35, 0xb4000
	s_mov_b32 s36, 0xc6000
	s_mov_b32 s37, 0xd8000
	s_mov_b32 s38, 0xea000
	s_mov_b32 s39, 0xfc000
	s_mov_b32 s40, 0x10e000
	s_mov_b32 s41, 0x120000
	s_mov_b32 s42, 0x132000
	s_mov_b32 s43, 0x144000
	s_mov_b32 s44, 0x156000
	s_mov_b32 s45, 0x168000
	s_mov_b32 s46, 0x17a000
	s_mov_b32 s47, 0x18c000
	s_mov_b32 s48, 0x19e000
	s_mov_b32 s49, 0x1b0000
	s_mov_b32 s50, 0x1c2000
	s_mov_b32 s51, 0x1d4000
	s_mov_b32 s52, 0x1e6000
	s_mov_b32 s53, 0x1f8000
	s_mov_b32 s54, 0x20a000
	s_mov_b32 s55, 0x21c000
	s_mov_b32 s56, 0x22e000
	s_movk_i32 s57, 0x2bff
	v_lshlrev_b32_e32 v2, 2, v2
	v_add_u32_e32 v19, 0x400, v18
	v_add_u32_e32 v20, 0x800, v18
	v_add_u32_e32 v21, 0xc00, v18
	v_add_u32_e32 v22, 0x1000, v18
	v_add_u32_e32 v23, 0x1400, v18
	v_add_u32_e32 v24, 0x1800, v18
	v_add_u32_e32 v25, 0x1c00, v18
	v_lshlrev_b32_e32 v4, 1, v4
	v_mov_b32_e32 v26, 5
	v_mov_b32_e32 v27, 3
	v_mov_b32_e32 v28, 6
	s_branch .LBB0_30

; #define LAS __attribute__((address_space(3)))
; DI void phase_norm(const Params& p, int l, const float* xin, LAS unsigned char* lds, int G, int bid) {
;     ...
;         for (int j = 0; j < 4; ++j) ss += (v[j].x * v[j].x + v[j].y * v[j].y) + (v[j].z * v[j].z + v[j].w * v[j].w);
;         const float rstd = 1.0f / sqrtf(wave_sum(ss) * (1.f / D) + EPS);
;         f32x4 g0 = {0.f, 0.f, 0.f, 0.f}, g1 = {0.f, 0.f, 0.f, 0.f};
;         unsigned long long* o8 = (unsigned long long*)(H + (size_t)row * D) + lane;
; #pragma unroll
;         for (int j = 0; j < 4; ++j) {
;             const int k = 256 * j + 4 * lane;
;             const f32x4 aa = *(const LAS f32x4*)(pa + b * 1024 + k), sh = *(const LAS f32x4*)(pb + b * 1024 + k);
.LBB0_142:
	s_or_b64 exec, exec, s[0:1]
	v_ashrrev_i32_e32 v0, 31, v178
	v_lshrrev_b32_e32 v0, 19, v0
	v_add_u32_e32 v0, v178, v0
	v_ashrrev_i32_e32 v178, 13, v0
	v_pk_mul_f32 v[186:187], v[158:159], v[158:159]
	v_pk_mul_f32 v[188:189], v[160:161], v[160:161]
	v_pk_fma_f32 v[186:187], v[154:155], v[154:155], v[186:187]
	v_pk_fma_f32 v[188:189], v[156:157], v[156:157], v[188:189]
	v_pk_fma_f32 v[186:187], v[150:151], v[150:151], v[186:187]
	v_pk_fma_f32 v[188:189], v[152:153], v[152:153], v[188:189]
	v_pk_fma_f32 v[186:187], v[146:147], v[146:147], v[186:187]
	v_pk_fma_f32 v[188:189], v[148:149], v[148:149], v[188:189]
	s_mov_b32 s0, 0xf800000
	v_lshl_add_u32 v178, v178, 12, v185
	ds_read_b128 v[222:225], v178
	ds_read_b128 v[226:229], v178 offset:16384
	ds_read_b128 v[230:233], v178 offset:1024
	ds_read_b128 v[234:237], v178 offset:17408
	ds_read_b128 v[238:241], v178 offset:2048
	ds_read_b128 v[242:245], v178 offset:18432
	v_pk_add_f32 v[186:187], v[186:187], v[188:189]
	s_nop 0
	v_add_f32_e32 v0, v186, v187
	v_lshl_add_u64 v[194:195], s[92:93], 0, v[172:173]
	s_nop 1
	v_add_f32_dpp v0, v0, v0 quad_perm:[1,0,3,2] row_mask:0xf bank_mask:0xf
	s_nop 1
	v_add_f32_dpp v0, v0, v0 quad_perm:[2,3,0,1] row_mask:0xf bank_mask:0xf
	s_nop 1
	v_add_f32_dpp v0, v0, v0 row_half_mirror row_mask:0xf bank_mask:0xf
	s_nop 1
	v_add_f32_dpp v0, v0, v0 row_mirror row_mask:0xf bank_mask:0xf
	s_nop 3
	v_readlane_b32 s17, v0, 0
	v_readlane_b32 s23, v0, 16
	v_readlane_b32 s28, v0, 32
	v_readlane_b32 s29, v0, 48
	s_nop 1
	v_mov_b32_e32 v0, s17
	v_mov_b32_e32 v186, s28
	v_add_f32_e32 v0, s23, v0
	v_add_f32_e32 v186, s29, v186
	v_add_f32_e32 v0, v0, v186
	v_fmamk_f32 v0, v0, 0x3a800000, v204
	v_cmp_gt_f32_e32 vcc, s0, v0
	v_mul_f32_e32 v186, 0x4f800000, v0
	s_nop 0
	v_cndmask_b32_e32 v0, v0, v186, vcc
	v_sqrt_f32_e32 v186, v0
	s_nop 0
	v_add_u32_e32 v187, -1, v186
	v_fma_f32 v188, -v187, v186, v0
	v_cmp_ge_f32_e64 s[0:1], 0, v188
	v_add_u32_e32 v188, 1, v186
	s_nop 0
	v_cndmask_b32_e64 v187, v186, v187, s[0:1]
	v_fma_f32 v186, -v188, v186, v0
	v_cmp_lt_f32_e64 s[0:1], 0, v186
	s_nop 1
	v_cndmask_b32_e64 v186, v187, v188, s[0:1]
	v_mul_f32_e32 v187, 0x37800000, v186
	v_cndmask_b32_e32 v186, v186, v187, vcc
	v_cmp_class_f32_e32 vcc, v0, v205
	s_nop 1
	v_cndmask_b32_e32 v0, v186, v0, vcc
	v_div_scale_f32 v186, s[0:1], v0, v0, 1.0
	v_rcp_f32_e32 v187, v186
	s_brev_b32 s0, 32
	v_fma_f32 v188, -v186, v187, 1.0
	v_fmac_f32_e32 v187, v188, v187
	v_div_scale_f32 v188, vcc, 1.0, v0, 1.0
	v_mul_f32_e32 v189, v188, v187
	v_fma_f32 v190, -v186, v189, v188
	v_fmac_f32_e32 v189, v190, v187
	v_fma_f32 v186, -v186, v189, v188
	v_div_fmas_f32 v186, v186, v187, v189
	v_div_fixup_f32 v0, v186, v0, 1.0


; #define LAS __attribute__((address_space(3)))
; DI void phase_norm(const Params& p, int l, const float* xin, LAS unsigned char* lds, int G, int bid) {
;     ...
;         for (int j = 0; j < 4; ++j) {
;             const int k = 256 * j + 4 * lane;
;             const f32x4 aa = *(const LAS f32x4*)(pa + b * 1024 + k), sh = *(const LAS f32x4*)(pb + b * 1024 + k);
;             const f32x4 h = (v[j] * rstd) * aa + sh;
; #pragma unroll
;             for (int e = 0; e < 4; ++e) { g0 += w0[j][e] * h[e]; g1 += w1[j][e] * h[e]; }
;             o8[64 * j] = (unsigned long long)cvt_pk_bf16(h.x, h.y) | ((unsigned long long)cvt_pk_bf16(h.z, h.w) << 32);
;         }
	v_pk_mul_f32 v[158:159], v[158:159], v[0:1] op_sel_hi:[1,0]
	v_pk_mul_f32 v[160:161], v[160:161], v[0:1] op_sel_hi:[1,0]
	v_pk_mul_f32 v[154:155], v[154:155], v[0:1] op_sel_hi:[1,0]
	v_pk_mul_f32 v[156:157], v[156:157], v[0:1] op_sel_hi:[1,0]
	s_waitcnt lgkmcnt(4)
	v_pk_fma_f32 v[158:159], v[222:223], v[158:159], v[226:227]
	v_pk_fma_f32 v[160:161], v[224:225], v[160:161], v[228:229]
	v_pk_fma_f32 v[186:187], v[14:15], v[158:159], 0 op_sel_hi:[1,0,0]
	v_pk_fma_f32 v[188:189], v[16:17], v[158:159], 0 op_sel_hi:[1,0,0]
	v_pk_fma_f32 v[186:187], v[6:7], v[158:159], v[186:187] op_sel:[0,1,0]
	v_pk_fma_f32 v[190:191], v[10:11], v[158:159], 0 op_sel_hi:[1,0,0]
	v_pk_fma_f32 v[192:193], v[12:13], v[158:159], 0 op_sel_hi:[1,0,0]
	v_pk_fma_f32 v[186:187], v[30:31], v[160:161], v[186:187] op_sel_hi:[1,0,1]
	v_pk_fma_f32 v[188:189], v[8:9], v[158:159], v[188:189] op_sel:[0,1,0]
	v_pk_fma_f32 v[192:193], v[4:5], v[158:159], v[192:193] op_sel:[0,1,0]
	v_pk_fma_f32 v[190:191], v[2:3], v[158:159], v[190:191] op_sel:[0,1,0]
	v_pk_fma_f32 v[198:199], v[22:23], v[160:161], v[186:187] op_sel:[0,1,0]
	v_cvt_pk_bf16_f32 v186, v158, v159
	v_add_co_u32_e32 v158, vcc, s0, v194
	v_cvt_pk_bf16_f32 v187, v160, v161
	s_nop 0
	v_addc_co_u32_e32 v159, vcc, 0, v195, vcc
	v_pk_fma_f32 v[188:189], v[32:33], v[160:161], v[188:189] op_sel_hi:[1,0,1]
	v_pk_fma_f32 v[190:191], v[26:27], v[160:161], v[190:191] op_sel_hi:[1,0,1]
	v_pk_fma_f32 v[192:193], v[28:29], v[160:161], v[192:193] op_sel_hi:[1,0,1]
	global_store_dwordx2 v[158:159], v[186:187], off
	v_pk_fma_f32 v[196:197], v[24:25], v[160:161], v[188:189] op_sel:[0,1,0]
	v_pk_fma_f32 v[200:201], v[20:21], v[160:161], v[192:193] op_sel:[0,1,0]
	v_pk_fma_f32 v[218:219], v[18:19], v[160:161], v[190:191] op_sel:[0,1,0]


; #define LAS __attribute__((address_space(3)))
; DI void phase_norm(const Params& p, int l, const float* xin, LAS unsigned char* lds, int G, int bid) {
;     ...
;         for (int j = 0; j < 4; ++j) {
;             const int k = 256 * j + 4 * lane;
;             const f32x4 aa = *(const LAS f32x4*)(pa + b * 1024 + k), sh = *(const LAS f32x4*)(pb + b * 1024 + k);
;             const f32x4 h = (v[j] * rstd) * aa + sh;
; #pragma unroll
;             for (int e = 0; e < 4; ++e) { g0 += w0[j][e] * h[e]; g1 += w1[j][e] * h[e]; }
;             o8[64 * j] = (unsigned long long)cvt_pk_bf16(h.x, h.y) | ((unsigned long long)cvt_pk_bf16(h.z, h.w) << 32);
;         }
	v_pk_mul_f32 v[150:151], v[150:151], v[0:1] op_sel_hi:[1,0]
	v_pk_mul_f32 v[152:153], v[152:153], v[0:1] op_sel_hi:[1,0]
	v_pk_mul_f32 v[146:147], v[146:147], v[0:1] op_sel_hi:[1,0]
	v_pk_mul_f32 v[148:149], v[148:149], v[0:1] op_sel_hi:[1,0]
	s_waitcnt lgkmcnt(2)
	v_pk_fma_f32 v[154:155], v[230:231], v[154:155], v[234:235]
	v_pk_fma_f32 v[156:157], v[232:233], v[156:157], v[236:237]
	s_waitcnt vmcnt(9)
	v_pk_fma_f32 v[160:161], v[94:95], v[154:155], v[198:199] op_sel_hi:[1,0,1]
	v_pk_fma_f32 v[186:187], v[96:97], v[154:155], v[196:197] op_sel_hi:[1,0,1]
	v_pk_fma_f32 v[188:189], v[90:91], v[154:155], v[218:219] op_sel_hi:[1,0,1]
	v_pk_fma_f32 v[190:191], v[92:93], v[154:155], v[200:201] op_sel_hi:[1,0,1]
	v_pk_fma_f32 v[186:187], v[88:89], v[154:155], v[186:187] op_sel:[0,1,0]
	v_pk_fma_f32 v[160:161], v[86:87], v[154:155], v[160:161] op_sel:[0,1,0]
	v_pk_fma_f32 v[190:191], v[84:85], v[154:155], v[190:191] op_sel:[0,1,0]
	v_pk_fma_f32 v[188:189], v[82:83], v[154:155], v[188:189] op_sel:[0,1,0]
	v_cvt_pk_bf16_f32 v154, v154, v155
	v_cvt_pk_bf16_f32 v155, v156, v157
	v_pk_fma_f32 v[160:161], v[34:35], v[156:157], v[160:161] op_sel_hi:[1,0,1]
	v_pk_fma_f32 v[186:187], v[36:37], v[156:157], v[186:187] op_sel_hi:[1,0,1]
	v_pk_fma_f32 v[188:189], v[46:47], v[156:157], v[188:189] op_sel_hi:[1,0,1]
	v_pk_fma_f32 v[190:191], v[48:49], v[156:157], v[190:191] op_sel_hi:[1,0,1]
	global_store_dwordx2 v[158:159], v[154:155], off offset:512
	v_pk_fma_f32 v[192:193], v[44:45], v[156:157], v[186:187] op_sel:[0,1,0]
	v_pk_fma_f32 v[160:161], v[42:43], v[156:157], v[160:161] op_sel:[0,1,0]
	v_pk_fma_f32 v[190:191], v[40:41], v[156:157], v[190:191] op_sel:[0,1,0]
	v_pk_fma_f32 v[194:195], v[38:39], v[156:157], v[188:189] op_sel:[0,1,0]


; #define LAS __attribute__((address_space(3)))
; DI void phase_norm(const Params& p, int l, const float* xin, LAS unsigned char* lds, int G, int bid) {
;     ...
;         for (int j = 0; j < 4; ++j) {
;             const int k = 256 * j + 4 * lane;
;             const f32x4 aa = *(const LAS f32x4*)(pa + b * 1024 + k), sh = *(const LAS f32x4*)(pb + b * 1024 + k);
;             const f32x4 h = (v[j] * rstd) * aa + sh;
; #pragma unroll
;             for (int e = 0; e < 4; ++e) { g0 += w0[j][e] * h[e]; g1 += w1[j][e] * h[e]; }
;             o8[64 * j] = (unsigned long long)cvt_pk_bf16(h.x, h.y) | ((unsigned long long)cvt_pk_bf16(h.z, h.w) << 32);
;         }
; #pragma unroll
;         for (int e = 0; e < 4; ++e) { g0[e] = wave_sum(g0[e]); g1[e] = wave_sum(g1[e]); }
;         if (lane == 0) { *(f32x4*)(gates + (size_t)row * 8) = g0; *(f32x4*)(gates + (size_t)row * 8 + 4) = g1; }
	s_waitcnt lgkmcnt(0)
	v_pk_fma_f32 v[150:151], v[238:239], v[150:151], v[242:243]
	v_pk_fma_f32 v[152:153], v[240:241], v[152:153], v[244:245]
	s_waitcnt vmcnt(6)
	v_pk_fma_f32 v[154:155], v[110:111], v[150:151], v[160:161] op_sel_hi:[1,0,1]
	v_pk_fma_f32 v[156:157], v[112:113], v[150:151], v[192:193] op_sel_hi:[1,0,1]
	v_pk_fma_f32 v[160:161], v[106:107], v[150:151], v[194:195] op_sel_hi:[1,0,1]
	v_pk_fma_f32 v[186:187], v[108:109], v[150:151], v[190:191] op_sel_hi:[1,0,1]
	v_pk_fma_f32 v[156:157], v[104:105], v[150:151], v[156:157] op_sel:[0,1,0]
	v_pk_fma_f32 v[154:155], v[102:103], v[150:151], v[154:155] op_sel:[0,1,0]
	v_pk_fma_f32 v[186:187], v[100:101], v[150:151], v[186:187] op_sel:[0,1,0]
	v_pk_fma_f32 v[160:161], v[98:99], v[150:151], v[160:161] op_sel:[0,1,0]
	v_cvt_pk_bf16_f32 v150, v150, v151
	v_cvt_pk_bf16_f32 v151, v152, v153
	v_pk_fma_f32 v[154:155], v[50:51], v[152:153], v[154:155] op_sel_hi:[1,0,1]
	v_pk_fma_f32 v[156:157], v[52:53], v[152:153], v[156:157] op_sel_hi:[1,0,1]
	v_pk_fma_f32 v[160:161], v[62:63], v[152:153], v[160:161] op_sel_hi:[1,0,1]
	v_pk_fma_f32 v[186:187], v[64:65], v[152:153], v[186:187] op_sel_hi:[1,0,1]
	global_store_dwordx2 v[158:159], v[150:151], off offset:1024
	v_pk_fma_f32 v[188:189], v[60:61], v[152:153], v[156:157] op_sel:[0,1,0]
	v_pk_fma_f32 v[190:191], v[58:59], v[152:153], v[154:155] op_sel:[0,1,0]
	v_pk_fma_f32 v[186:187], v[56:57], v[152:153], v[186:187] op_sel:[0,1,0]
	v_pk_fma_f32 v[160:161], v[54:55], v[152:153], v[160:161] op_sel:[0,1,0]
	ds_read_b128 v[150:153], v178 offset:3072
	ds_read_b128 v[154:157], v178 offset:19456
	s_waitcnt lgkmcnt(0)
	v_pk_fma_f32 v[146:147], v[146:147], v[150:151], v[154:155]
	s_waitcnt vmcnt(3)
	v_pk_fma_f32 v[150:151], v[126:127], v[146:147], v[190:191] op_sel_hi:[1,0,1]
	v_pk_fma_f32 v[148:149], v[148:149], v[152:153], v[156:157]
	v_pk_fma_f32 v[150:151], v[118:119], v[146:147], v[150:151] op_sel:[0,1,0]
	v_pk_fma_f32 v[152:153], v[128:129], v[146:147], v[188:189] op_sel_hi:[1,0,1]
	v_pk_fma_f32 v[154:155], v[122:123], v[146:147], v[160:161] op_sel_hi:[1,0,1]
	v_pk_fma_f32 v[156:157], v[124:125], v[146:147], v[186:187] op_sel_hi:[1,0,1]
	v_pk_fma_f32 v[150:151], v[66:67], v[148:149], v[150:151] op_sel_hi:[1,0,1]
	v_pk_fma_f32 v[152:153], v[120:121], v[146:147], v[152:153] op_sel:[0,1,0]
	v_pk_fma_f32 v[156:157], v[116:117], v[146:147], v[156:157] op_sel:[0,1,0]
	v_pk_fma_f32 v[154:155], v[114:115], v[146:147], v[154:155] op_sel:[0,1,0]
	v_pk_fma_f32 v[160:161], v[74:75], v[148:149], v[150:151] op_sel:[0,1,0]
	v_cvt_pk_bf16_f32 v146, v146, v147
	v_cvt_pk_bf16_f32 v147, v148, v149
	global_store_dwordx2 v[158:159], v[146:147], off offset:1536
	v_pk_fma_f32 v[152:153], v[68:69], v[148:149], v[152:153] op_sel_hi:[1,0,1]
	v_pk_fma_f32 v[154:155], v[78:79], v[148:149], v[154:155] op_sel_hi:[1,0,1]
	v_pk_fma_f32 v[156:157], v[80:81], v[148:149], v[156:157] op_sel_hi:[1,0,1]
	v_pk_fma_f32 v[152:153], v[76:77], v[148:149], v[152:153] op_sel:[0,1,0]
	v_pk_fma_f32 v[150:151], v[72:73], v[148:149], v[156:157] op_sel:[0,1,0]
	v_pk_fma_f32 v[154:155], v[70:71], v[148:149], v[154:155] op_sel:[0,1,0]
	s_nop 1
	v_permlane32_swap_b32 v160, v154
	v_permlane32_swap_b32 v161, v155
	v_permlane32_swap_b32 v152, v150
	v_permlane32_swap_b32 v153, v151
	v_pk_add_f32 v[160:161], v[160:161], v[154:155]
	v_pk_add_f32 v[152:153], v[152:153], v[150:151]
	s_nop 1
	v_permlane16_swap_b32 v160, v152
	v_permlane16_swap_b32 v161, v153
	v_pk_add_f32 v[160:161], v[160:161], v[152:153]
	v_add_u32_e32 v146, v176, v221
	s_nop 0
	v_add_f32_dpp v160, v160, v160 quad_perm:[1,0,3,2] row_mask:0xf bank_mask:0xf
	v_add_f32_dpp v161, v161, v161 quad_perm:[1,0,3,2] row_mask:0xf bank_mask:0xf
	s_nop 0
	v_add_f32_dpp v160, v160, v160 quad_perm:[2,3,0,1] row_mask:0xf bank_mask:0xf
	v_add_f32_dpp v161, v161, v161 quad_perm:[2,3,0,1] row_mask:0xf bank_mask:0xf
	s_nop 0
	v_add_f32_dpp v160, v160, v160 row_half_mirror row_mask:0xf bank_mask:0xf
	v_add_f32_dpp v161, v161, v161 row_half_mirror row_mask:0xf bank_mask:0xf
	s_nop 0
	v_add_f32_dpp v160, v160, v160 row_mirror row_mask:0xf bank_mask:0xf
	v_add_f32_dpp v161, v161, v161 row_mirror row_mask:0xf bank_mask:0xf
	s_and_saveexec_b64 s[0:1], s[40:41]
	global_store_dwordx2 v146, v[160:161], s[92:93]
	s_branch .LBB0_139
